# P2: each workgroup drains only its own XCD queue (no scan of the 7 other queues at the end)
# baseline (speedup 1.0000x reference)
; __device__ __forceinline__ void p2_mixers(CArgs& a0, LAS unsigned char* lds, int tid, int lane, int wid, int rep) {
;     ...
;     for (int qi = 0; qi < 8; ++qi) {
;         const int qx = (int)((xcc + (unsigned)qi) & 7u);
;         unsigned* queue = (unsigned*)(ws0 + WS_CTL) + CW_QUEUE + 64 * (qx + 8 * rep);
;         if (qi > 0 && tid == 0) { unsigned v = __hip_atomic_load(queue, __ATOMIC_RELAXED, __HIP_MEMORY_SCOPE_AGENT);
;             if (v < (unsigned)P2_PER_XCD) v = __hip_atomic_fetch_add(queue, 1u, __ATOMIC_RELAXED, __HIP_MEMORY_SCOPE_AGENT); *slot = v; }
;         __syncthreads();
;         int it_cur = __builtin_amdgcn_readfirstlane((int)*slot);
;         __syncthreads();
.LBB0_319:
	s_add_i32 s80, s80, 1
	s_add_i32 s3, s3, 1
	s_add_i32 s82, s82, 1
	s_cmp_lg_u32 s80, 1
	s_cbranch_scc0 .LBB0_654
